# cost-weighted VALU spacing: attention finishSM interleave with 4 issue-slots per qkt MFMA gap (rest after the last MFMA)
# speedup vs baseline: 1.0040x; 1.0006x over previous
; #define LAS __attribute__((address_space(3)))
; __device__ __forceinline__ void finishSM(f32x16& p0, f32x16& p1, float alpha, float& l_reg, bf16x8& pa0, bf16x8& pa1, bf16x8& pa2, bf16x8& pa3) {
; #pragma unroll
;     for (int r = 0; r < 16; ++r) p1[r] = __builtin_amdgcn_exp2f(p1[r]);
;     float ps = 0;
; #pragma unroll
;     for (int r = 0; r < 16; ++r) ps += p0[r];
; #pragma unroll
;     for (int r = 0; r < 16; ++r) ps += p1[r];
;     { auto rr = __builtin_amdgcn_permlane32_swap(__float_as_uint(ps), __float_as_uint(ps), false, false);
;       ps = __uint_as_float(rr[0]) + __uint_as_float(rr[1]); }
;     l_reg = l_reg * alpha + ps;
;     ...
;     PK4(p0, 0, pa0); PK4(p0, 8, pa1); PK4(p1, 0, pa2); PK4(p1, 8, pa3);
;     ...
; }
; template <int KB>
; __device__ __forceinline__ void qkt(f32x16& p0, f32x16& p1, lptr K_lds, int r32, int hi, const bf16x8* qr) {
;     p0 = f32x16{}; p1 = f32x16{};
;     lptr kb[4];
; #pragma unroll
;     for (int dd = 0; dd < 4; ++dd) kb[dd] = K_lds + KB * SHM_K + KSWZ(r32, (dd * 16 + hi * 8) * 2);
; #pragma unroll
;     for (int d0 = 0; d0 < 8; ++d0) { lptr a = kb[d0 & 3] + (d0 >> 2) * 128;
;         bf16x8 b0 = *reinterpret_cast<const LAS bf16x8*>(a);
;         bf16x8 b1 = *reinterpret_cast<const LAS bf16x8*>(a + 32 * 256);
;         p0 = __builtin_amdgcn_mfma_f32_32x32x16_bf16(b0, qr[d0], p0, 0, 0, 0);
;         p1 = __builtin_amdgcn_mfma_f32_32x32x16_bf16(b1, qr[d0], p1, 0, 0, 0); }
; }
.LBB0_865:
	ds_read_b128 v[82:85], v187 offset:49152
	ds_read_b128 v[86:89], v187 offset:57344
	ds_read_b128 v[236:239], v185 offset:49152
	ds_read_b128 v[240:243], v185 offset:57344
	s_waitcnt lgkmcnt(3)
	v_mfma_f32_32x32x16_bf16 v[98:113], v[82:85], v[142:145], 0
	v_exp_f32_e32 v80, v80
	v_exp_f32_e32 v1, v1
	s_waitcnt lgkmcnt(2)
	v_mfma_f32_32x32x16_bf16 v[82:97], v[86:89], v[142:145], 0
	v_exp_f32_e32 v78, v78
	v_exp_f32_e32 v79, v79
	s_waitcnt lgkmcnt(0)
	v_mfma_f32_32x32x16_bf16 v[82:97], v[240:243], v[138:141], v[82:97]
	v_exp_f32_e32 v76, v76
	v_exp_f32_e32 v77, v77
	v_mfma_f32_32x32x16_bf16 v[98:113], v[236:239], v[138:141], v[98:113]
	v_exp_f32_e32 v81, v74
	v_exp_f32_e32 v146, v75
	ds_read_b128 v[236:239], v184 offset:49152
	ds_read_b128 v[240:243], v184 offset:57344
	s_waitcnt lgkmcnt(0)
	v_mfma_f32_32x32x16_bf16 v[82:97], v[240:243], v[134:137], v[82:97]
	v_exp_f32_e32 v226, v72
	v_exp_f32_e32 v233, v66
	v_mfma_f32_32x32x16_bf16 v[98:113], v[236:239], v[134:137], v[98:113]
	v_add_f32_e32 v66, 0, v160
	v_add_f32_e32 v66, v227, v66
	v_add_f32_e32 v66, v158, v66
	v_add_f32_e32 v66, v161, v66
	ds_read_b128 v[236:239], v183 offset:49152
	ds_read_b128 v[240:243], v183 offset:57344
	s_waitcnt lgkmcnt(0)
	v_mfma_f32_32x32x16_bf16 v[82:97], v[240:243], v[130:133], v[82:97]
	v_add_f32_e32 v66, v157, v66
	v_add_f32_e32 v66, v159, v66
	v_add_f32_e32 v66, v155, v66
	v_add_f32_e32 v66, v156, v66
	v_mfma_f32_32x32x16_bf16 v[98:113], v[236:239], v[130:133], v[98:113]
	v_add_f32_e32 v66, v152, v66
	v_add_f32_e32 v66, v154, v66
	v_add_f32_e32 v66, v151, v66
	v_add_f32_e32 v66, v153, v66
	ds_read_b128 v[236:239], v187 offset:49280
	ds_read_b128 v[240:243], v187 offset:57472
	s_waitcnt lgkmcnt(0)
	v_mfma_f32_32x32x16_bf16 v[82:97], v[240:243], v[126:129], v[82:97]
	v_add_f32_e32 v66, v148, v66
	v_add_f32_e32 v66, v150, v66
	v_add_f32_e32 v66, v147, v66
	v_add_f32_e32 v66, v149, v66
	v_mfma_f32_32x32x16_bf16 v[98:113], v[236:239], v[126:129], v[98:113]
	v_add_f32_e32 v66, v80, v66
	v_add_f32_e32 v66, v1, v66
	v_add_f32_e32 v66, v78, v66
	v_add_f32_e32 v66, v79, v66
	ds_read_b128 v[236:239], v185 offset:49280
	ds_read_b128 v[240:243], v185 offset:57472
	s_waitcnt lgkmcnt(0)
	v_mfma_f32_32x32x16_bf16 v[82:97], v[240:243], v[122:125], v[82:97]
	v_add_f32_e32 v66, v76, v66
	v_exp_f32_e32 v228, v73
	v_add_f32_e32 v66, v77, v66
	v_mfma_f32_32x32x16_bf16 v[98:113], v[236:239], v[122:125], v[98:113]
	v_exp_f32_e32 v229, v70
	v_add_f32_e32 v66, v81, v66
	ds_read_b128 v[236:239], v184 offset:49280
	ds_read_b128 v[240:243], v184 offset:57472
	s_waitcnt lgkmcnt(0)
	v_mfma_f32_32x32x16_bf16 v[82:97], v[240:243], v[118:121], v[82:97]
	v_exp_f32_e32 v230, v71
	v_add_f32_e32 v66, v146, v66
	v_mfma_f32_32x32x16_bf16 v[98:113], v[236:239], v[118:121], v[98:113]
	v_exp_f32_e32 v231, v68
	v_add_f32_e32 v66, v226, v66
	ds_read_b128 v[236:239], v183 offset:49280
	ds_read_b128 v[240:243], v183 offset:57472
	s_waitcnt lgkmcnt(0)
	v_mfma_f32_32x32x16_bf16 v[82:97], v[240:243], v[114:117], v[82:97]
	v_exp_f32_e32 v232, v69
	v_add_f32_e32 v66, v228, v66
	v_add_f32_e32 v66, v229, v66
	v_mfma_f32_32x32x16_bf16 v[98:113], v[236:239], v[114:117], v[98:113]
	v_exp_f32_e32 v234, v67
	v_add_f32_e32 v66, v230, v66
	v_add_f32_e32 v66, v231, v66
	v_add_f32_e32 v66, v232, v66
	v_add_f32_e32 v66, v233, v66
	v_add_f32_e32 v224, v234, v66
	v_mov_b32_e32 v225, v224
	v_cvt_pk_bf16_f32 v66, v160, v227
	v_cvt_pk_bf16_f32 v67, v158, v161
	v_cvt_pk_bf16_f32 v68, v157, v159
	v_cvt_pk_bf16_f32 v69, v155, v156
	v_cvt_pk_bf16_f32 v70, v152, v154
	v_cvt_pk_bf16_f32 v71, v151, v153
	v_cvt_pk_bf16_f32 v72, v148, v150
	v_cvt_pk_bf16_f32 v73, v147, v149
	v_cvt_pk_bf16_f32 v74, v80, v1
	v_cvt_pk_bf16_f32 v75, v78, v79
	v_cvt_pk_bf16_f32 v76, v76, v77
	v_cvt_pk_bf16_f32 v77, v81, v146
	v_cvt_pk_bf16_f32 v78, v226, v228
	v_cvt_pk_bf16_f32 v79, v229, v230
	v_cvt_pk_bf16_f32 v80, v231, v232
	v_cvt_pk_bf16_f32 v81, v233, v234
	s_nop 1
	v_permlane32_swap_b32_e32 v224, v225
	v_permlane32_swap_b32_e32 v66, v68
	v_permlane32_swap_b32_e32 v67, v69
	v_permlane32_swap_b32_e32 v70, v72
	v_permlane32_swap_b32_e32 v71, v73
	v_permlane32_swap_b32_e32 v74, v76
	v_permlane32_swap_b32_e32 v75, v77
	v_permlane32_swap_b32_e32 v78, v80
	v_permlane32_swap_b32_e32 v79, v81
	v_add_u32_e32 v227, s89, v186
	v_add_u32_e32 v146, 1, v227
	v_add_u32_e32 v148, 33, v227
	v_ashrrev_i32_e32 v147, 31, v146
	v_ashrrev_i32_e32 v149, 31, v148
	v_lshlrev_b64 v[154:155], 8, v[146:147]
	v_lshlrev_b64 v[156:157], 8, v[148:149]
	v_lshl_add_u64 v[146:147], v[176:177], 0, v[154:155]
	v_lshl_add_u64 v[150:151], v[176:177], 0, v[156:157]
	v_lshl_add_u64 v[154:155], v[178:179], 0, v[154:155]
	v_lshl_add_u64 v[158:159], v[178:179], 0, v[156:157]
	global_load_dwordx4 v[146:149], v[146:147], off
	s_nop 0
	global_load_dwordx4 v[150:153], v[150:151], off
	s_nop 0
	global_load_dwordx4 v[154:157], v[154:155], off
	s_nop 0
	global_load_dwordx4 v[158:161], v[158:159], off
	ds_read_b64_tr_b16 v[228:229], v181 offset:0
	ds_read_b64_tr_b16 v[230:231], v181 offset:0x800
	ds_read_b64_tr_b16 v[232:233], v181 offset:0x1000
	ds_read_b64_tr_b16 v[234:235], v181 offset:0x1800
	ds_read_b64_tr_b16 v[236:237], v181 offset:0x2000
	ds_read_b64_tr_b16 v[238:239], v181 offset:0x2800
	ds_read_b64_tr_b16 v[240:241], v181 offset:0x3000
	ds_read_b64_tr_b16 v[242:243], v181 offset:0x3800
	s_waitcnt lgkmcnt(0)
; #define LAS __attribute__((address_space(3)))
; __device__ __forceinline__ void bias_tile(f32x16& p0, f32x16& p1, const LAS float* cs) {
; #pragma unroll
;     for (int i = 0; i < 4; ++i) { const f32x4 a = *(const LAS f32x4*)(cs + 8 * i), b = *(const LAS f32x4*)(cs + 32 + 8 * i);
; #pragma unroll
;         for (int j = 0; j < 4; ++j) { p0[4 * i + j] = fmaf(p0[4 * i + j], C2, a[j]); p1[4 * i + j] = fmaf(p1[4 * i + j], C2, b[j]); } }
; }
; template <int VB>
; __device__ __forceinline__ void pv_tile(f32x16* o, int vb0, bf16x8 pa0, bf16x8 pa1, bf16x8 pa2, bf16x8 pa3) {
;     ...
;     PV_D0(0); PV_D0(1); PV_D0(2); PV_D0(3);
	s_nop 0
	v_mfma_f32_32x32x16_bf16 v[50:65], v[66:69], v[228:231], v[50:65]
	ds_read_b64_tr_b16 v[228:229], v181 offset:0x200
	ds_read_b64_tr_b16 v[230:231], v181 offset:0xa00
	v_mfma_f32_32x32x16_bf16 v[50:65], v[70:73], v[232:235], v[50:65]
	ds_read_b64_tr_b16 v[232:233], v181 offset:0x1200
	ds_read_b64_tr_b16 v[234:235], v181 offset:0x1a00
	v_mfma_f32_32x32x16_bf16 v[50:65], v[74:77], v[236:239], v[50:65]
	ds_read_b64_tr_b16 v[236:237], v181 offset:0x2200
	ds_read_b64_tr_b16 v[238:239], v181 offset:0x2a00
	v_mfma_f32_32x32x16_bf16 v[50:65], v[78:81], v[240:243], v[50:65]
	ds_read_b64_tr_b16 v[240:241], v181 offset:0x3200
	ds_read_b64_tr_b16 v[242:243], v181 offset:0x3a00
	s_waitcnt lgkmcnt(0)
	v_mfma_f32_32x32x16_bf16 v[34:49], v[66:69], v[228:231], v[34:49]
	ds_read_b64_tr_b16 v[228:229], v181 offset:0x400
	ds_read_b64_tr_b16 v[230:231], v181 offset:0xc00
	v_mfma_f32_32x32x16_bf16 v[34:49], v[70:73], v[232:235], v[34:49]
	ds_read_b64_tr_b16 v[232:233], v181 offset:0x1400
	ds_read_b64_tr_b16 v[234:235], v181 offset:0x1c00
	v_mfma_f32_32x32x16_bf16 v[34:49], v[74:77], v[236:239], v[34:49]
	ds_read_b64_tr_b16 v[236:237], v181 offset:0x2400
	ds_read_b64_tr_b16 v[238:239], v181 offset:0x2c00
	v_mfma_f32_32x32x16_bf16 v[34:49], v[78:81], v[240:243], v[34:49]
	ds_read_b64_tr_b16 v[240:241], v181 offset:0x3400
	ds_read_b64_tr_b16 v[242:243], v181 offset:0x3c00
	s_waitcnt lgkmcnt(0)
	v_mfma_f32_32x32x16_bf16 v[18:33], v[66:69], v[228:231], v[18:33]
	ds_read_b64_tr_b16 v[228:229], v181 offset:0x600
	ds_read_b64_tr_b16 v[230:231], v181 offset:0xe00
	v_mfma_f32_32x32x16_bf16 v[18:33], v[70:73], v[232:235], v[18:33]
	ds_read_b64_tr_b16 v[232:233], v181 offset:0x1600
	ds_read_b64_tr_b16 v[234:235], v181 offset:0x1e00
	v_mfma_f32_32x32x16_bf16 v[18:33], v[74:77], v[236:239], v[18:33]
	ds_read_b64_tr_b16 v[236:237], v181 offset:0x2600
	ds_read_b64_tr_b16 v[238:239], v181 offset:0x2e00
	v_mfma_f32_32x32x16_bf16 v[18:33], v[78:81], v[240:243], v[18:33]
	ds_read_b64_tr_b16 v[240:241], v181 offset:0x3600
	ds_read_b64_tr_b16 v[242:243], v181 offset:0x3e00
	s_waitcnt lgkmcnt(0)
	v_mfma_f32_32x32x16_bf16 v[2:17], v[66:69], v[228:231], v[2:17]
	s_cmp_le_i32 s89, s80
	v_mfma_f32_32x32x16_bf16 v[2:17], v[70:73], v[232:235], v[2:17]
	v_mfma_f32_32x32x16_bf16 v[2:17], v[74:77], v[236:239], v[2:17]
	v_mfma_f32_32x32x16_bf16 v[2:17], v[78:81], v[240:243], v[2:17]
	ds_read_b128 v[228:231], v223 offset:128
	ds_read_b128 v[78:81], v223
	ds_read_b128 v[70:73], v223 offset:32
	ds_read_b128 v[232:235], v223 offset:160
	ds_read_b128 v[74:77], v223 offset:64
	ds_read_b128 v[236:239], v223 offset:192
	ds_read_b128 v[240:243], v223 offset:96
	ds_read_b128 v[244:247], v223 offset:224
	s_waitcnt lgkmcnt(6)
	v_pk_fma_f32 v[100:101], v[100:101], s[2:3], v[80:81] op_sel_hi:[1,0,1]
	s_waitcnt lgkmcnt(3)
	v_pk_fma_f32 v[68:69], v[106:107], s[2:3], v[74:75] op_sel_hi:[1,0,1]
	v_pk_fma_f32 v[74:75], v[102:103], s[2:3], v[70:71] op_sel_hi:[1,0,1]
	s_waitcnt lgkmcnt(1)
	v_pk_fma_f32 v[66:67], v[110:111], s[2:3], v[240:241] op_sel_hi:[1,0,1]
	v_pk_fma_f32 v[70:71], v[112:113], s[2:3], v[242:243] op_sel_hi:[1,0,1]
	v_pk_fma_f32 v[76:77], v[108:109], s[2:3], v[76:77] op_sel_hi:[1,0,1]
	v_pk_fma_f32 v[102:103], v[104:105], s[2:3], v[72:73] op_sel_hi:[1,0,1]
	v_pk_fma_f32 v[98:99], v[98:99], s[2:3], v[78:79] op_sel_hi:[1,0,1]
	s_waitcnt lgkmcnt(0)
	v_pk_fma_f32 v[72:73], v[94:95], s[2:3], v[244:245] op_sel_hi:[1,0,1]
	v_pk_fma_f32 v[78:79], v[90:91], s[2:3], v[236:237] op_sel_hi:[1,0,1]
	v_pk_fma_f32 v[86:87], v[86:87], s[2:3], v[232:233] op_sel_hi:[1,0,1]
	v_pk_fma_f32 v[80:81], v[96:97], s[2:3], v[246:247] op_sel_hi:[1,0,1]
	v_pk_fma_f32 v[90:91], v[92:93], s[2:3], v[238:239] op_sel_hi:[1,0,1]
	v_pk_fma_f32 v[88:89], v[88:89], s[2:3], v[234:235] op_sel_hi:[1,0,1]
	v_pk_fma_f32 v[84:85], v[84:85], s[2:3], v[230:231] op_sel_hi:[1,0,1]
	v_pk_fma_f32 v[82:83], v[82:83], s[2:3], v[228:229] op_sel_hi:[1,0,1]
	s_cbranch_scc1 .LBB0_867
; __device__ __forceinline__ void mask_tile(f32x16& p0, f32x16& p1, int dq) {
;     const float NEG = -__builtin_inff();
; #pragma unroll
;     for (int r = 0; r < 16; ++r) { const int c = (r & 3) + 8 * (r >> 2);
;         if (dq - c < 0) p0[r] = NEG;
;         if (dq - c - 32 < 0) p1[r] = NEG; }
; }
	v_add_u32_e32 v1, 64, v222
	v_cmp_gt_i32_e64 s[70:71], 26, v1
	v_cmp_gt_i32_e64 s[72:73], 27, v1
	v_cmp_gt_i32_e64 s[68:69], 25, v1
	s_and_b64 s[70:71], s[72:73], s[70:71]
	v_cmp_gt_i32_e64 s[66:67], 24, v1
	s_and_b64 s[68:69], s[70:71], s[68:69]
	v_cmp_gt_i32_e64 s[64:65], 19, v1
	s_and_b64 s[66:67], s[68:69], s[66:67]
	v_cmp_gt_i32_e64 s[62:63], 18, v1
	s_and_b64 s[64:65], s[66:67], s[64:65]
	v_cmp_gt_i32_e64 s[60:61], 17, v1
	s_and_b64 s[62:63], s[64:65], s[62:63]
	v_cmp_gt_i32_e64 s[58:59], 16, v1
	s_and_b64 s[60:61], s[62:63], s[60:61]
	v_cmp_gt_i32_e64 s[56:57], 11, v1
	s_and_b64 s[58:59], s[60:61], s[58:59]
	v_cmp_gt_i32_e64 s[54:55], 10, v1
	s_and_b64 s[56:57], s[58:59], s[56:57]
	v_cmp_gt_i32_e64 s[52:53], 9, v1
	s_and_b64 s[54:55], s[56:57], s[54:55]
	v_cmp_gt_i32_e64 s[50:51], 8, v1
	s_and_b64 s[52:53], s[54:55], s[52:53]
	v_cmp_gt_i32_e64 s[48:49], 3, v1
	s_and_b64 s[50:51], s[52:53], s[50:51]
	v_cmp_gt_i32_e64 s[46:47], 2, v1
	s_and_b64 s[48:49], s[50:51], s[48:49]
	v_cmp_gt_i32_e64 s[44:45], 1, v1
	s_and_b64 s[46:47], s[48:49], s[46:47]
	v_cmp_gt_i32_e64 s[42:43], 0, v1
	s_and_b64 s[44:45], s[46:47], s[44:45]
	s_and_b64 s[42:43], s[44:45], s[42:43]
	v_cmp_gt_i32_e64 s[38:39], 58, v1
	v_cndmask_b32_e64 v98, v98, v206, s[42:43]
	v_cmp_gt_i32_e64 s[42:43], 59, v1
	v_cmp_gt_i32_e64 s[36:37], 57, v1
	s_and_b64 s[38:39], s[42:43], s[38:39]
	v_cmp_gt_i32_e64 s[34:35], 56, v1
	s_and_b64 s[36:37], s[38:39], s[36:37]
	v_cmp_gt_i32_e64 s[30:31], 51, v1
	s_and_b64 s[34:35], s[36:37], s[34:35]
	v_cmp_gt_i32_e64 s[28:29], 50, v1
	s_and_b64 s[30:31], s[34:35], s[30:31]
	v_cmp_gt_i32_e64 s[26:27], 49, v1
	s_and_b64 s[28:29], s[30:31], s[28:29]
	v_cmp_gt_i32_e64 s[24:25], 48, v1
	s_and_b64 s[26:27], s[28:29], s[26:27]
	v_cmp_gt_i32_e64 s[22:23], 43, v1
	s_and_b64 s[24:25], s[26:27], s[24:25]
	v_cmp_gt_i32_e64 s[20:21], 42, v1
	s_and_b64 s[22:23], s[24:25], s[22:23]
	v_cmp_gt_i32_e64 s[18:19], 41, v1
	s_and_b64 s[20:21], s[22:23], s[20:21]
	v_cmp_gt_i32_e64 s[16:17], 40, v1
	s_and_b64 s[18:19], s[20:21], s[18:19]
	v_cmp_gt_i32_e64 s[14:15], 35, v1
	s_and_b64 s[16:17], s[18:19], s[16:17]
	v_cmp_gt_i32_e64 s[12:13], 34, v1
	s_and_b64 s[14:15], s[16:17], s[14:15]
	v_cmp_gt_i32_e64 s[10:11], 33, v1
	s_and_b64 s[12:13], s[14:15], s[12:13]
	v_cmp_gt_i32_e32 vcc, 32, v1
	s_and_b64 s[10:11], s[12:13], s[10:11]
	s_and_b64 vcc, s[10:11], vcc
	v_cndmask_b32_e64 v71, v71, v206, s[72:73]
	v_cndmask_b32_e64 v70, v70, v206, s[70:71]
	v_cndmask_b32_e64 v67, v67, v206, s[68:69]
	v_cndmask_b32_e64 v66, v66, v206, s[66:67]
	v_cndmask_b32_e64 v77, v77, v206, s[64:65]
	v_cndmask_b32_e64 v76, v76, v206, s[62:63]
	v_cndmask_b32_e64 v69, v69, v206, s[60:61]
	v_cndmask_b32_e64 v68, v68, v206, s[58:59]
	v_cndmask_b32_e64 v103, v103, v206, s[56:57]
	v_cndmask_b32_e64 v102, v102, v206, s[54:55]
	v_cndmask_b32_e64 v75, v75, v206, s[52:53]
	v_cndmask_b32_e64 v74, v74, v206, s[50:51]
	v_cndmask_b32_e64 v101, v101, v206, s[48:49]
	v_cndmask_b32_e64 v100, v100, v206, s[46:47]
	v_cndmask_b32_e64 v99, v99, v206, s[44:45]
	v_cndmask_b32_e64 v81, v81, v206, s[42:43]
	v_cndmask_b32_e64 v80, v80, v206, s[38:39]
	v_cndmask_b32_e64 v73, v73, v206, s[36:37]
	v_cndmask_b32_e64 v72, v72, v206, s[34:35]
	v_cndmask_b32_e64 v91, v91, v206, s[30:31]
	v_cndmask_b32_e64 v90, v90, v206, s[28:29]
	v_cndmask_b32_e64 v79, v79, v206, s[26:27]
	v_cndmask_b32_e64 v78, v78, v206, s[24:25]
	v_cndmask_b32_e64 v89, v89, v206, s[22:23]
	v_cndmask_b32_e64 v88, v88, v206, s[20:21]
	v_cndmask_b32_e64 v87, v87, v206, s[18:19]
	v_cndmask_b32_e64 v86, v86, v206, s[16:17]
	v_cndmask_b32_e64 v85, v85, v206, s[14:15]
	v_cndmask_b32_e64 v84, v84, v206, s[12:13]
	v_cndmask_b32_e64 v83, v83, v206, s[10:11]
	v_cndmask_b32_e32 v82, v82, v206, vcc

; #define LAS __attribute__((address_space(3)))
; __device__ __forceinline__ void partialSM(f32x16& p0, f32x16& p1, float& m_reg, float& alpha) {
;     float pmax = p0[0];
; #pragma unroll
;     for (int r = 1; r < 16; ++r) pmax = fmaxf(pmax, p0[r]);
; #pragma unroll
;     for (int r = 0; r < 16; ++r) pmax = fmaxf(pmax, p1[r]);
;     { auto rr = __builtin_amdgcn_permlane32_swap(__float_as_uint(pmax), __float_as_uint(pmax), false, false);
;       pmax = fmaxf(__uint_as_float(rr[0]), __uint_as_float(rr[1])); }
;     float mn;
;     if (__builtin_expect(__all(pmax - m_reg <= THR2), 1)) { mn = m_reg; alpha = 1.f; }
;     else { mn = fmaxf(m_reg, pmax); alpha = __builtin_amdgcn_exp2f(m_reg - mn); m_reg = mn; }
; #pragma unroll
;     for (int r = 0; r < 16; ++r) p0[r] = p0[r] - mn;
; #pragma unroll
;     for (int r = 0; r < 16; ++r) p1[r] = p1[r] - mn;
; #pragma unroll
;     for (int r = 0; r < 16; ++r) p0[r] = __builtin_amdgcn_exp2f(p0[r]);
; }
; __device__ __forceinline__ void finishSM(f32x16& p0, f32x16& p1, float alpha, float& l_reg, bf16x8& pa0, bf16x8& pa1, bf16x8& pa2, bf16x8& pa3) {
; #pragma unroll
;     for (int r = 0; r < 16; ++r) p1[r] = __builtin_amdgcn_exp2f(p1[r]);
;     float ps = 0;
; #pragma unroll
;     for (int r = 0; r < 16; ++r) ps += p0[r];
; #pragma unroll
;     for (int r = 0; r < 16; ++r) ps += p1[r];
;     { auto rr = __builtin_amdgcn_permlane32_swap(__float_as_uint(ps), __float_as_uint(ps), false, false);
;       ps = __uint_as_float(rr[0]) + __uint_as_float(rr[1]); }
;     l_reg = l_reg * alpha + ps;
;     ...
;     PK4(p0, 0, pa0); PK4(p0, 8, pa1); PK4(p1, 0, pa2); PK4(p1, 8, pa3);
;     ...
; }
; template <int KB>
; __device__ __forceinline__ void qkt(f32x16& p0, f32x16& p1, lptr K_lds, int r32, int hi, const bf16x8* qr) {
;     p0 = f32x16{}; p1 = f32x16{};
;     lptr kb[4];
; #pragma unroll
;     for (int dd = 0; dd < 4; ++dd) kb[dd] = K_lds + KB * SHM_K + KSWZ(r32, (dd * 16 + hi * 8) * 2);
; #pragma unroll
;     for (int d0 = 0; d0 < 8; ++d0) { lptr a = kb[d0 & 3] + (d0 >> 2) * 128;
;         bf16x8 b0 = *reinterpret_cast<const LAS bf16x8*>(a);
;         bf16x8 b1 = *reinterpret_cast<const LAS bf16x8*>(a + 32 * 256);
;         p0 = __builtin_amdgcn_mfma_f32_32x32x16_bf16(b0, qr[d0], p0, 0, 0, 0);
;         p1 = __builtin_amdgcn_mfma_f32_32x32x16_bf16(b1, qr[d0], p1, 0, 0, 0); }
; }
.LBB0_871:
	v_cndmask_b32_e64 v1, v1, v220, s[10:11]
	v_sub_f32_e32 v92, v98, v1
	v_sub_f32_e32 v93, v99, v1
	v_sub_f32_e32 v94, v100, v1
	v_sub_f32_e32 v95, v101, v1
	v_sub_f32_e32 v74, v74, v1
	v_sub_f32_e32 v75, v75, v1
	v_sub_f32_e32 v96, v102, v1
	v_sub_f32_e32 v97, v103, v1
	v_sub_f32_e32 v68, v68, v1
	v_sub_f32_e32 v69, v69, v1
	v_sub_f32_e32 v76, v76, v1
	v_sub_f32_e32 v77, v77, v1
	v_sub_f32_e32 v66, v66, v1
	v_sub_f32_e32 v67, v67, v1
	v_sub_f32_e32 v70, v70, v1
	v_sub_f32_e32 v71, v71, v1
	v_exp_f32_e32 v98, v92
	v_exp_f32_e32 v113, v93
	v_exp_f32_e32 v99, v94
	v_exp_f32_e32 v112, v95
	v_exp_f32_e32 v100, v74
	v_exp_f32_e32 v111, v75
	v_exp_f32_e32 v101, v96
	v_exp_f32_e32 v110, v97
	v_exp_f32_e32 v102, v68
	v_exp_f32_e32 v109, v69
	v_exp_f32_e32 v103, v76
	v_exp_f32_e32 v108, v77
	v_exp_f32_e32 v104, v66
	v_exp_f32_e32 v107, v67
	v_exp_f32_e32 v105, v70
	v_exp_f32_e32 v106, v71
	v_sub_f32_e32 v220, v82, v1
	v_sub_f32_e32 v236, v83, v1
	v_sub_f32_e32 v237, v84, v1
	v_sub_f32_e32 v238, v85, v1
	v_sub_f32_e32 v239, v86, v1
	v_sub_f32_e32 v240, v87, v1
	v_sub_f32_e32 v241, v88, v1
	v_sub_f32_e32 v242, v89, v1
	v_sub_f32_e32 v243, v78, v1
	v_sub_f32_e32 v244, v79, v1
	v_sub_f32_e32 v245, v90, v1
	v_sub_f32_e32 v246, v91, v1
	v_sub_f32_e32 v247, v72, v1
	v_sub_f32_e32 v248, v73, v1
	v_sub_f32_e32 v249, v80, v1
	v_sub_f32_e32 v250, v81, v1
	s_waitcnt lgkmcnt(0)
	s_barrier
	ds_read_b128 v[66:69], v187 offset:32768
	ds_read_b128 v[70:73], v187 offset:40960
	ds_read_b128 v[146:149], v185 offset:32768
	ds_read_b128 v[150:153], v185 offset:40960
	s_waitcnt lgkmcnt(3)
	v_mfma_f32_32x32x16_bf16 v[82:97], v[66:69], v[142:145], 0
	v_exp_f32_e32 v220, v220
	v_add_f32_e32 v228, 0, v98
	v_add_f32_e32 v228, v113, v228
	s_waitcnt lgkmcnt(2)
	v_mfma_f32_32x32x16_bf16 v[66:81], v[70:73], v[142:145], 0
	v_add_f32_e32 v228, v99, v228
	v_add_f32_e32 v228, v112, v228
	v_add_f32_e32 v228, v100, v228
	v_add_f32_e32 v228, v111, v228
	s_waitcnt lgkmcnt(1)
	v_mfma_f32_32x32x16_bf16 v[82:97], v[146:149], v[138:141], v[82:97]
	v_add_f32_e32 v228, v101, v228
	v_add_f32_e32 v228, v110, v228
	v_add_f32_e32 v228, v102, v228
	v_add_f32_e32 v228, v109, v228
	s_waitcnt lgkmcnt(0)
	v_mfma_f32_32x32x16_bf16 v[66:81], v[150:153], v[138:141], v[66:81]
	v_add_f32_e32 v228, v103, v228
	v_add_f32_e32 v228, v108, v228
	v_add_f32_e32 v228, v104, v228
	ds_read_b128 v[146:149], v184 offset:32768
	ds_read_b128 v[150:153], v184 offset:40960
	s_waitcnt lgkmcnt(1)
	v_mfma_f32_32x32x16_bf16 v[82:97], v[146:149], v[134:137], v[82:97]
	v_exp_f32_e32 v230, v236
	v_add_f32_e32 v228, v107, v228
	s_waitcnt lgkmcnt(0)
	v_mfma_f32_32x32x16_bf16 v[66:81], v[150:153], v[134:137], v[66:81]
	v_exp_f32_e32 v231, v237
	v_add_f32_e32 v228, v105, v228
	ds_read_b128 v[146:149], v183 offset:32768
	ds_read_b128 v[150:153], v183 offset:40960
	s_waitcnt lgkmcnt(1)
	v_mfma_f32_32x32x16_bf16 v[82:97], v[146:149], v[130:133], v[82:97]
	v_exp_f32_e32 v232, v238
	v_add_f32_e32 v228, v106, v228
	s_waitcnt lgkmcnt(0)
	v_mfma_f32_32x32x16_bf16 v[66:81], v[150:153], v[130:133], v[66:81]
	v_exp_f32_e32 v233, v239
	v_add_f32_e32 v228, v220, v228
	ds_read_b128 v[146:149], v187 offset:32896
	ds_read_b128 v[150:153], v187 offset:41088
	s_waitcnt lgkmcnt(1)
	v_mfma_f32_32x32x16_bf16 v[82:97], v[146:149], v[126:129], v[82:97]
	v_exp_f32_e32 v234, v240
	v_add_f32_e32 v228, v230, v228
	s_waitcnt lgkmcnt(0)
	v_mfma_f32_32x32x16_bf16 v[66:81], v[150:153], v[126:129], v[66:81]
	v_exp_f32_e32 v235, v241
	v_add_f32_e32 v228, v231, v228
	ds_read_b128 v[146:149], v185 offset:32896
	ds_read_b128 v[150:153], v185 offset:41088
	s_waitcnt lgkmcnt(1)
	v_mfma_f32_32x32x16_bf16 v[82:97], v[146:149], v[122:125], v[82:97]
	v_exp_f32_e32 v236, v242
	v_add_f32_e32 v228, v232, v228
	s_waitcnt lgkmcnt(0)
	v_mfma_f32_32x32x16_bf16 v[66:81], v[150:153], v[122:125], v[66:81]
	v_exp_f32_e32 v237, v243
	v_add_f32_e32 v228, v233, v228
	ds_read_b128 v[146:149], v184 offset:32896
	ds_read_b128 v[150:153], v184 offset:41088
	s_waitcnt lgkmcnt(1)
	v_mfma_f32_32x32x16_bf16 v[82:97], v[146:149], v[118:121], v[82:97]
	v_exp_f32_e32 v238, v244
	v_add_f32_e32 v228, v234, v228
	s_waitcnt lgkmcnt(0)
	v_mfma_f32_32x32x16_bf16 v[66:81], v[150:153], v[118:121], v[66:81]
	v_exp_f32_e32 v239, v245
	v_add_f32_e32 v228, v235, v228
	ds_read_b128 v[146:149], v183 offset:32896
	ds_read_b128 v[150:153], v183 offset:41088
	s_waitcnt lgkmcnt(1)
	v_mfma_f32_32x32x16_bf16 v[82:97], v[146:149], v[114:117], v[82:97]
	v_exp_f32_e32 v240, v246
	v_add_f32_e32 v228, v236, v228
	s_waitcnt lgkmcnt(0)
	v_mfma_f32_32x32x16_bf16 v[66:81], v[150:153], v[114:117], v[66:81]
	v_exp_f32_e32 v241, v247
	v_add_f32_e32 v228, v237, v228
	v_exp_f32_e32 v242, v248
	v_add_f32_e32 v228, v238, v228
	v_exp_f32_e32 v243, v249
	v_add_f32_e32 v228, v239, v228
	v_exp_f32_e32 v244, v250
	v_add_f32_e32 v228, v240, v228
	v_add_f32_e32 v228, v241, v228
	v_add_f32_e32 v228, v242, v228
	v_add_f32_e32 v228, v243, v228
	v_add_f32_e32 v228, v244, v228
	v_mov_b32_e32 v229, v228
	v_cvt_pk_bf16_f32 v98, v98, v113
	v_cvt_pk_bf16_f32 v99, v99, v112
	v_cvt_pk_bf16_f32 v100, v100, v111
	v_cvt_pk_bf16_f32 v101, v101, v110
	v_cvt_pk_bf16_f32 v102, v102, v109
	v_cvt_pk_bf16_f32 v103, v103, v108
	v_cvt_pk_bf16_f32 v104, v104, v107
	v_cvt_pk_bf16_f32 v105, v105, v106
	v_cvt_pk_bf16_f32 v106, v220, v230
	v_cvt_pk_bf16_f32 v107, v231, v232
	v_cvt_pk_bf16_f32 v108, v233, v234
	v_cvt_pk_bf16_f32 v109, v235, v236
	v_cvt_pk_bf16_f32 v110, v237, v238
	v_cvt_pk_bf16_f32 v111, v239, v240
	v_cvt_pk_bf16_f32 v112, v241, v242
	v_cvt_pk_bf16_f32 v113, v243, v244
	s_nop 1
	v_permlane32_swap_b32_e32 v228, v229
	v_permlane32_swap_b32_e32 v98, v100
	v_permlane32_swap_b32_e32 v99, v101
	v_permlane32_swap_b32_e32 v102, v104
	v_permlane32_swap_b32_e32 v103, v105
	v_permlane32_swap_b32_e32 v106, v108
	v_permlane32_swap_b32_e32 v107, v109
	v_permlane32_swap_b32_e32 v110, v112
	v_permlane32_swap_b32_e32 v111, v113
	s_add_i32 s10, s88, 1
	s_cmp_lt_i32 s10, s81
	s_cselect_b64 s[40:41], -1, 0
	s_cmp_ge_i32 s10, s81
	s_cbranch_scc1 .LBB0_873
	v_add_u32_e32 v146, 0x41, v227
	v_add_u32_e32 v148, 0x61, v227
	v_ashrrev_i32_e32 v147, 31, v146
	v_ashrrev_i32_e32 v149, 31, v148
	v_lshlrev_b64 v[154:155], 8, v[146:147]
	v_lshlrev_b64 v[156:157], 8, v[148:149]
	v_lshl_add_u64 v[146:147], v[176:177], 0, v[154:155]
	v_lshl_add_u64 v[150:151], v[176:177], 0, v[156:157]
	v_lshl_add_u64 v[154:155], v[178:179], 0, v[154:155]
	v_lshl_add_u64 v[158:159], v[178:179], 0, v[156:157]
	global_load_dwordx4 v[146:149], v[146:147], off
	s_nop 0
	global_load_dwordx4 v[150:153], v[150:151], off
	s_nop 0
	global_load_dwordx4 v[154:157], v[154:155], off
	s_nop 0
	global_load_dwordx4 v[158:161], v[158:159], off
